# in-proj epilogue: rope table in LDS re-laid out (80-byte row stride, two half-tables) so ds_read_b128 groups are bank-conflict free (was 4-way)
# speedup vs baseline: 1.0075x; 1.0032x over previous
.LBB0_131:
	s_or_b64 exec, exec, s[4:5]
	v_mov_b32_e32 v8, v198
	s_waitcnt lgkmcnt(0)
	s_barrier
	v_lshlrev_b32_e32 v249, 4, v198
	s_add_u32 s88, s44, 0x40000
	s_addc_u32 s89, s45, 0
	global_load_dwordx4 v[250:253], v249, s[88:89]
	v_lshrrev_b32_e32 v254, 3, v198
	v_mul_u32_u24_e32 v254, 0x50, v254
	v_and_b32_e32 v255, 3, v198
	v_lshl_add_u32 v254, v255, 4, v254
	v_bfe_u32 v255, v198, 2, 1
	v_mul_u32_u24_e32 v255, 0x1400, v255
	v_add_u32_e32 v254, v254, v255
	v_add_u32_e32 v254, 0x20400, v254
	v_bfe_u32 v249, v198, 4, 1
	v_mul_u32_u24_e32 v249, 0x1400, v249
	v_add_u32_e32 v249, 0x20400, v249
	s_waitcnt vmcnt(0)
	ds_write_b128 v254, v[250:253]
	s_waitcnt lgkmcnt(0)
	s_cmpk_gt_i32 s2, 0xfff
	v_readfirstlane_b32 s14, v8
	s_cbranch_scc0 .LBB0_134
	s_mov_b64 s[6:7], 0
	s_cmpk_gt_u32 s2, 0x10bf
	s_mov_b64 s[4:5], 0
	s_cbranch_scc1 .LBB0_135
	s_add_i32 s3, s2, 0xfffff000
	s_cmpk_lt_u32 s3, 0x80
	s_cselect_b32 s4, 4, 8
	s_lshr_b32 s3, s3, 4
	s_add_i32 s22, s4, s3
	s_and_b32 s3, s2, 15
	s_or_b32 s24, s3, 0x80
	s_mov_b64 s[4:5], -1
	s_branch .LBB0_135

.LBB0_176:
	s_lshr_b32 s15, s15, 6
	s_add_i32 s15, s15, s69
	v_mov_b32_e32 v164, s15
	v_cndmask_b32_e64 v164, v174, v164, s[4:5]
	v_lshlrev_b32_e32 v164, 4, v164
	v_ashrrev_i32_e32 v165, 31, v164
	s_andn2_b64 vcc, exec, s[36:37]
	v_mad_u32_u24 v164, v164, 5, v249
	s_cbranch_vccnz .LBB0_180
	s_cmp_eq_u32 s13, 1
	s_cbranch_scc0 .LBB0_179
	ds_read_b128 v[166:169], v164
	ds_read_b128 v[170:173], v164 offset:16
	ds_read_b128 v[182:185], v164 offset:32
	ds_read_b128 v[186:189], v164 offset:48
	v_and_b32_e32 v192, 64, v181
	v_xor_b32_e32 v191, 32, v181
	v_add_u32_e32 v192, 64, v192
	v_cmp_lt_i32_e32 vcc, v191, v192
	v_mov_b32_e32 v190, v123
	s_waitcnt lgkmcnt(0)
	v_mov_b32_e32 v201, v168
	v_cndmask_b32_e32 v191, v181, v191, vcc
	v_lshlrev_b32_e32 v191, 2, v191
	ds_bpermute_b32 v194, v191, v126
	ds_bpermute_b32 v195, v191, v127
	ds_bpermute_b32 v199, v191, v122
	ds_bpermute_b32 v123, v191, v123
	ds_bpermute_b32 v192, v191, v124
	ds_bpermute_b32 v193, v191, v125
	ds_bpermute_b32 v196, v191, v120
	ds_bpermute_b32 v197, v191, v121
	s_waitcnt lgkmcnt(6)
	v_pk_mul_f32 v[194:195], v[140:141], v[194:195]
	s_waitcnt lgkmcnt(5)
	v_mul_f32_e32 v199, v140, v199
	s_waitcnt lgkmcnt(4)
	v_mul_f32_e32 v191, v140, v123
	v_mov_b32_e32 v168, v167
	v_mov_b32_e32 v167, v172
	v_mov_b32_e32 v172, v171
	s_waitcnt lgkmcnt(2)
	v_pk_mul_f32 v[192:193], v[140:141], v[192:193]
	s_waitcnt lgkmcnt(0)
	v_pk_mul_f32 v[196:197], v[140:141], v[196:197]
	v_mov_b32_e32 v200, v166
	v_mov_b32_e32 v166, v170
	v_pk_mul_f32 v[170:171], v[194:195], v[172:173]
	v_mov_b32_e32 v172, v182
	v_mov_b32_e32 v173, v184
	v_mov_b32_e32 v184, v183
	v_mul_f32_e32 v122, v122, v186
	v_mul_f32_e32 v182, v199, v187
	v_pk_mul_f32 v[186:187], v[190:191], v[188:189]
	v_pk_mul_f32 v[168:169], v[192:193], v[168:169]
	v_pk_mul_f32 v[184:185], v[196:197], v[184:185]
	v_mov_b32_e32 v123, v186
	v_mov_b32_e32 v183, v187
	v_pk_fma_f32 v[124:125], v[124:125], v[200:201], v[168:169]
	v_pk_fma_f32 v[126:127], v[126:127], v[166:167], v[170:171]
	v_pk_fma_f32 v[120:121], v[120:121], v[172:173], v[184:185]
	v_pk_add_f32 v[122:123], v[122:123], v[182:183]
	v_pk_mul_f32 v[168:169], s[22:23], v[126:127] op_sel_hi:[0,1]
	v_pk_mul_f32 v[166:167], s[22:23], v[124:125] op_sel_hi:[0,1]
	v_pk_mul_f32 v[172:173], s[22:23], v[122:123] op_sel_hi:[0,1]
	v_pk_mul_f32 v[170:171], s[22:23], v[120:121] op_sel_hi:[0,1]
	s_branch .LBB0_180

.LBB0_188:
	v_mov_b32_e32 v112, s15
	v_cndmask_b32_e64 v112, v176, v112, s[4:5]
	v_lshlrev_b32_e32 v112, 4, v112
	v_ashrrev_i32_e32 v113, 31, v112
	s_andn2_b64 vcc, exec, s[28:29]
	v_mad_u32_u24 v112, v112, 5, v249
	s_cbranch_vccnz .LBB0_192
	s_cmp_eq_u32 s13, 1
	s_cbranch_scc0 .LBB0_191
	ds_read_b128 v[114:117], v112
	ds_read_b128 v[122:125], v112 offset:16
	ds_read_b128 v[164:167], v112 offset:32
	ds_read_b128 v[168:171], v112 offset:48
	v_and_b32_e32 v126, 64, v181
	v_xor_b32_e32 v119, 32, v181
	v_add_u32_e32 v126, 64, v126
	v_cmp_lt_i32_e32 vcc, v119, v126
	v_mov_b32_e32 v118, v107
	s_waitcnt lgkmcnt(0)
	v_mov_b32_e32 v185, v116
	v_cndmask_b32_e32 v119, v181, v119, vcc
	v_lshlrev_b32_e32 v119, 2, v119
	ds_bpermute_b32 v172, v119, v110
	ds_bpermute_b32 v173, v119, v111
	ds_bpermute_b32 v107, v119, v107
	ds_bpermute_b32 v126, v119, v108
	ds_bpermute_b32 v127, v119, v109
	ds_bpermute_b32 v182, v119, v104
	ds_bpermute_b32 v183, v119, v105
	ds_bpermute_b32 v184, v119, v106
	s_waitcnt lgkmcnt(6)
	v_pk_mul_f32 v[172:173], v[140:141], v[172:173]
	s_waitcnt lgkmcnt(5)
	v_mul_f32_e32 v119, v140, v107
	v_mov_b32_e32 v116, v115
	v_mov_b32_e32 v115, v124
	v_mov_b32_e32 v124, v123
	s_waitcnt lgkmcnt(3)
	v_pk_mul_f32 v[126:127], v[140:141], v[126:127]
	s_waitcnt lgkmcnt(1)
	v_pk_mul_f32 v[182:183], v[140:141], v[182:183]
	s_waitcnt lgkmcnt(0)
	v_mul_f32_e32 v186, v140, v184
	v_mov_b32_e32 v184, v114
	v_mov_b32_e32 v114, v122
	v_pk_mul_f32 v[122:123], v[172:173], v[124:125]
	v_mov_b32_e32 v125, v166
	v_mov_b32_e32 v166, v165
	v_pk_mul_f32 v[118:119], v[118:119], v[170:171]
	v_pk_mul_f32 v[116:117], v[126:127], v[116:117]
	v_mov_b32_e32 v124, v164
	v_mul_f32_e32 v106, v106, v168
	v_mul_f32_e32 v126, v186, v169
	v_pk_mul_f32 v[164:165], v[182:183], v[166:167]
	v_mov_b32_e32 v107, v118
	v_mov_b32_e32 v127, v119
	v_pk_fma_f32 v[108:109], v[108:109], v[184:185], v[116:117]
	v_pk_fma_f32 v[110:111], v[110:111], v[114:115], v[122:123]
	v_pk_fma_f32 v[104:105], v[104:105], v[124:125], v[164:165]
	v_pk_add_f32 v[106:107], v[106:107], v[126:127]
	v_pk_mul_f32 v[116:117], s[22:23], v[110:111] op_sel_hi:[0,1]
	v_pk_mul_f32 v[114:115], s[22:23], v[108:109] op_sel_hi:[0,1]
	v_pk_mul_f32 v[122:123], s[22:23], v[106:107] op_sel_hi:[0,1]
	v_pk_mul_f32 v[118:119], s[22:23], v[104:105] op_sel_hi:[0,1]
	s_branch .LBB0_192

.LBB0_200:
	v_mov_b32_e32 v96, s15
	v_cndmask_b32_e64 v96, v177, v96, s[4:5]
	v_lshlrev_b32_e32 v96, 4, v96
	v_ashrrev_i32_e32 v97, 31, v96
	s_andn2_b64 vcc, exec, s[28:29]
	v_mad_u32_u24 v96, v96, 5, v249
	s_cbranch_vccnz .LBB0_204
	s_cmp_eq_u32 s13, 1
	s_cbranch_scc0 .LBB0_203
	ds_read_b128 v[98:101], v96
	ds_read_b128 v[102:105], v96 offset:16
	ds_read_b128 v[106:109], v96 offset:32
	ds_read_b128 v[110:113], v96 offset:48
	v_and_b32_e32 v116, 64, v181
	v_xor_b32_e32 v115, 32, v181
	v_add_u32_e32 v116, 64, v116
	v_cmp_lt_i32_e32 vcc, v115, v116
	v_mov_b32_e32 v114, v91
	s_waitcnt lgkmcnt(0)
	v_mov_b32_e32 v125, v100
	v_cndmask_b32_e32 v115, v181, v115, vcc
	v_lshlrev_b32_e32 v115, 2, v115
	ds_bpermute_b32 v118, v115, v94
	ds_bpermute_b32 v119, v115, v95
	ds_bpermute_b32 v124, v115, v90
	ds_bpermute_b32 v91, v115, v91
	ds_bpermute_b32 v116, v115, v92
	ds_bpermute_b32 v117, v115, v93
	ds_bpermute_b32 v122, v115, v88
	ds_bpermute_b32 v123, v115, v89
	s_waitcnt lgkmcnt(6)
	v_pk_mul_f32 v[118:119], v[140:141], v[118:119]
	s_waitcnt lgkmcnt(5)
	v_mul_f32_e32 v126, v140, v124
	s_waitcnt lgkmcnt(4)
	v_mul_f32_e32 v115, v140, v91
	v_mov_b32_e32 v100, v99
	v_mov_b32_e32 v99, v104
	v_mov_b32_e32 v104, v103
	s_waitcnt lgkmcnt(2)
	v_pk_mul_f32 v[116:117], v[140:141], v[116:117]
	s_waitcnt lgkmcnt(0)
	v_pk_mul_f32 v[122:123], v[140:141], v[122:123]
	v_mov_b32_e32 v124, v98
	v_mov_b32_e32 v98, v102
	v_pk_mul_f32 v[102:103], v[118:119], v[104:105]
	v_mov_b32_e32 v104, v106
	v_mov_b32_e32 v105, v108
	v_mov_b32_e32 v108, v107
	v_mul_f32_e32 v90, v90, v110
	v_mul_f32_e32 v106, v126, v111
	v_pk_mul_f32 v[110:111], v[114:115], v[112:113]
	v_pk_mul_f32 v[100:101], v[116:117], v[100:101]
	v_pk_mul_f32 v[108:109], v[122:123], v[108:109]
	v_mov_b32_e32 v91, v110
	v_mov_b32_e32 v107, v111
	v_pk_fma_f32 v[92:93], v[92:93], v[124:125], v[100:101]
	v_pk_fma_f32 v[94:95], v[94:95], v[98:99], v[102:103]
	v_pk_fma_f32 v[88:89], v[88:89], v[104:105], v[108:109]
	v_pk_add_f32 v[90:91], v[90:91], v[106:107]
	v_pk_mul_f32 v[100:101], s[22:23], v[94:95] op_sel_hi:[0,1]
	v_pk_mul_f32 v[98:99], s[22:23], v[92:93] op_sel_hi:[0,1]
	v_pk_mul_f32 v[104:105], s[22:23], v[90:91] op_sel_hi:[0,1]
	v_pk_mul_f32 v[102:103], s[22:23], v[88:89] op_sel_hi:[0,1]
	s_branch .LBB0_204

.LBB0_212:
	v_mov_b32_e32 v80, s15
	v_cndmask_b32_e64 v80, v179, v80, s[4:5]
	v_lshlrev_b32_e32 v80, 4, v80
	v_ashrrev_i32_e32 v81, 31, v80
	s_andn2_b64 vcc, exec, s[28:29]
	v_mad_u32_u24 v80, v80, 5, v249
	s_cbranch_vccnz .LBB0_216
	s_cmp_eq_u32 s13, 1
	s_cbranch_scc0 .LBB0_215
	ds_read_b128 v[82:85], v80
	ds_read_b128 v[86:89], v80 offset:16
	ds_read_b128 v[90:93], v80 offset:32
	ds_read_b128 v[94:97], v80 offset:48
	v_and_b32_e32 v100, 64, v181
	v_xor_b32_e32 v99, 32, v181
	v_add_u32_e32 v100, 64, v100
	v_cmp_lt_i32_e32 vcc, v99, v100
	v_mov_b32_e32 v98, v75
	s_waitcnt lgkmcnt(0)
	v_mov_b32_e32 v107, v84
	v_cndmask_b32_e32 v99, v181, v99, vcc
	v_lshlrev_b32_e32 v99, 2, v99
	ds_bpermute_b32 v102, v99, v78
	ds_bpermute_b32 v103, v99, v79
	ds_bpermute_b32 v106, v99, v74
	ds_bpermute_b32 v75, v99, v75
	ds_bpermute_b32 v100, v99, v76
	ds_bpermute_b32 v101, v99, v77
	ds_bpermute_b32 v104, v99, v72
	ds_bpermute_b32 v105, v99, v73
	s_waitcnt lgkmcnt(6)
	v_pk_mul_f32 v[102:103], v[140:141], v[102:103]
	s_waitcnt lgkmcnt(5)
	v_mul_f32_e32 v108, v140, v106
	s_waitcnt lgkmcnt(4)
	v_mul_f32_e32 v99, v140, v75
	v_mov_b32_e32 v84, v83
	v_mov_b32_e32 v83, v88
	v_mov_b32_e32 v88, v87
	s_waitcnt lgkmcnt(2)
	v_pk_mul_f32 v[100:101], v[140:141], v[100:101]
	s_waitcnt lgkmcnt(0)
	v_pk_mul_f32 v[104:105], v[140:141], v[104:105]
	v_mov_b32_e32 v106, v82
	v_mov_b32_e32 v82, v86
	v_pk_mul_f32 v[86:87], v[102:103], v[88:89]
	v_mov_b32_e32 v88, v90
	v_mov_b32_e32 v89, v92
	v_mov_b32_e32 v92, v91
	v_mul_f32_e32 v74, v74, v94
	v_mul_f32_e32 v90, v108, v95
	v_pk_mul_f32 v[94:95], v[98:99], v[96:97]
	v_pk_mul_f32 v[84:85], v[100:101], v[84:85]
	v_pk_mul_f32 v[92:93], v[104:105], v[92:93]
	v_mov_b32_e32 v75, v94
	v_mov_b32_e32 v91, v95
	v_pk_fma_f32 v[76:77], v[76:77], v[106:107], v[84:85]
	v_pk_fma_f32 v[78:79], v[78:79], v[82:83], v[86:87]
	v_pk_fma_f32 v[72:73], v[72:73], v[88:89], v[92:93]
	v_pk_add_f32 v[74:75], v[74:75], v[90:91]
	v_pk_mul_f32 v[84:85], s[22:23], v[78:79] op_sel_hi:[0,1]
	v_pk_mul_f32 v[82:83], s[22:23], v[76:77] op_sel_hi:[0,1]
	v_pk_mul_f32 v[88:89], s[22:23], v[74:75] op_sel_hi:[0,1]
	v_pk_mul_f32 v[86:87], s[22:23], v[72:73] op_sel_hi:[0,1]
	s_branch .LBB0_216

.LBB0_224:
	s_add_i32 s15, s15, 2
	v_mov_b32_e32 v64, s15
	v_cndmask_b32_e64 v64, v174, v64, s[4:5]
	v_lshlrev_b32_e32 v64, 4, v64
	v_ashrrev_i32_e32 v65, 31, v64
	s_andn2_b64 vcc, exec, s[28:29]
	v_mad_u32_u24 v64, v64, 5, v249
	s_cbranch_vccnz .LBB0_228
	s_cmp_eq_u32 s13, 1
	s_cbranch_scc0 .LBB0_227
	ds_read_b128 v[66:69], v64
	ds_read_b128 v[70:73], v64 offset:16
	ds_read_b128 v[74:77], v64 offset:32
	ds_read_b128 v[78:81], v64 offset:48
	v_and_b32_e32 v84, 64, v181
	v_xor_b32_e32 v83, 32, v181
	v_add_u32_e32 v84, 64, v84
	v_cmp_lt_i32_e32 vcc, v83, v84
	v_mov_b32_e32 v82, v59
	s_waitcnt lgkmcnt(0)
	v_mov_b32_e32 v91, v68
	v_cndmask_b32_e32 v83, v181, v83, vcc
	v_lshlrev_b32_e32 v83, 2, v83
	ds_bpermute_b32 v86, v83, v62
	ds_bpermute_b32 v87, v83, v63
	ds_bpermute_b32 v90, v83, v58
	ds_bpermute_b32 v59, v83, v59
	ds_bpermute_b32 v84, v83, v60
	ds_bpermute_b32 v85, v83, v61
	ds_bpermute_b32 v88, v83, v56
	ds_bpermute_b32 v89, v83, v57
	s_waitcnt lgkmcnt(6)
	v_pk_mul_f32 v[86:87], v[140:141], v[86:87]
	s_waitcnt lgkmcnt(5)
	v_mul_f32_e32 v92, v140, v90
	s_waitcnt lgkmcnt(4)
	v_mul_f32_e32 v83, v140, v59
	v_mov_b32_e32 v68, v67
	v_mov_b32_e32 v67, v72
	v_mov_b32_e32 v72, v71
	s_waitcnt lgkmcnt(2)
	v_pk_mul_f32 v[84:85], v[140:141], v[84:85]
	s_waitcnt lgkmcnt(0)
	v_pk_mul_f32 v[88:89], v[140:141], v[88:89]
	v_mov_b32_e32 v90, v66
	v_mov_b32_e32 v66, v70
	v_pk_mul_f32 v[70:71], v[86:87], v[72:73]
	v_mov_b32_e32 v72, v74
	v_mov_b32_e32 v73, v76
	v_mov_b32_e32 v76, v75
	v_mul_f32_e32 v58, v58, v78
	v_mul_f32_e32 v74, v92, v79
	v_pk_mul_f32 v[78:79], v[82:83], v[80:81]
	v_pk_mul_f32 v[68:69], v[84:85], v[68:69]
	v_pk_mul_f32 v[76:77], v[88:89], v[76:77]
	v_mov_b32_e32 v59, v78
	v_mov_b32_e32 v75, v79
	v_pk_fma_f32 v[60:61], v[60:61], v[90:91], v[68:69]
	v_pk_fma_f32 v[62:63], v[62:63], v[66:67], v[70:71]
	v_pk_fma_f32 v[56:57], v[56:57], v[72:73], v[76:77]
	v_pk_add_f32 v[58:59], v[58:59], v[74:75]
	v_pk_mul_f32 v[68:69], s[22:23], v[62:63] op_sel_hi:[0,1]
	v_pk_mul_f32 v[66:67], s[22:23], v[60:61] op_sel_hi:[0,1]
	v_pk_mul_f32 v[72:73], s[22:23], v[58:59] op_sel_hi:[0,1]
	v_pk_mul_f32 v[70:71], s[22:23], v[56:57] op_sel_hi:[0,1]
	s_branch .LBB0_228

.LBB0_236:
	v_mov_b32_e32 v48, s15
	v_cndmask_b32_e64 v48, v176, v48, s[4:5]
	v_lshlrev_b32_e32 v48, 4, v48
	v_ashrrev_i32_e32 v49, 31, v48
	s_andn2_b64 vcc, exec, s[28:29]
	v_mad_u32_u24 v48, v48, 5, v249
	s_cbranch_vccnz .LBB0_240
	s_cmp_eq_u32 s13, 1
	s_cbranch_scc0 .LBB0_239
	ds_read_b128 v[50:53], v48
	ds_read_b128 v[54:57], v48 offset:16
	ds_read_b128 v[58:61], v48 offset:32
	ds_read_b128 v[62:65], v48 offset:48
	v_and_b32_e32 v68, 64, v181
	v_xor_b32_e32 v67, 32, v181
	v_add_u32_e32 v68, 64, v68
	v_cmp_lt_i32_e32 vcc, v67, v68
	v_mov_b32_e32 v66, v43
	s_waitcnt lgkmcnt(0)
	v_mov_b32_e32 v75, v52
	v_cndmask_b32_e32 v67, v181, v67, vcc
	v_lshlrev_b32_e32 v67, 2, v67
	ds_bpermute_b32 v70, v67, v46
	ds_bpermute_b32 v71, v67, v47
	ds_bpermute_b32 v74, v67, v42
	ds_bpermute_b32 v43, v67, v43
	ds_bpermute_b32 v68, v67, v44
	ds_bpermute_b32 v69, v67, v45
	ds_bpermute_b32 v72, v67, v40
	ds_bpermute_b32 v73, v67, v41
	s_waitcnt lgkmcnt(6)
	v_pk_mul_f32 v[70:71], v[140:141], v[70:71]
	s_waitcnt lgkmcnt(5)
	v_mul_f32_e32 v76, v140, v74
	s_waitcnt lgkmcnt(4)
	v_mul_f32_e32 v67, v140, v43
	v_mov_b32_e32 v52, v51
	v_mov_b32_e32 v51, v56
	v_mov_b32_e32 v56, v55
	s_waitcnt lgkmcnt(2)
	v_pk_mul_f32 v[68:69], v[140:141], v[68:69]
	s_waitcnt lgkmcnt(0)
	v_pk_mul_f32 v[72:73], v[140:141], v[72:73]
	v_mov_b32_e32 v74, v50
	v_mov_b32_e32 v50, v54
	v_pk_mul_f32 v[54:55], v[70:71], v[56:57]
	v_mov_b32_e32 v56, v58
	v_mov_b32_e32 v57, v60
	v_mov_b32_e32 v60, v59
	v_mul_f32_e32 v42, v42, v62
	v_mul_f32_e32 v58, v76, v63
	v_pk_mul_f32 v[62:63], v[66:67], v[64:65]
	v_pk_mul_f32 v[52:53], v[68:69], v[52:53]
	v_pk_mul_f32 v[60:61], v[72:73], v[60:61]
	v_mov_b32_e32 v43, v62
	v_mov_b32_e32 v59, v63
	v_pk_fma_f32 v[44:45], v[44:45], v[74:75], v[52:53]
	v_pk_fma_f32 v[46:47], v[46:47], v[50:51], v[54:55]
	v_pk_fma_f32 v[40:41], v[40:41], v[56:57], v[60:61]
	v_pk_add_f32 v[42:43], v[42:43], v[58:59]
	v_pk_mul_f32 v[52:53], s[22:23], v[46:47] op_sel_hi:[0,1]
	v_pk_mul_f32 v[50:51], s[22:23], v[44:45] op_sel_hi:[0,1]
	v_pk_mul_f32 v[56:57], s[22:23], v[42:43] op_sel_hi:[0,1]
	v_pk_mul_f32 v[54:55], s[22:23], v[40:41] op_sel_hi:[0,1]
	s_branch .LBB0_240

.LBB0_248:
	v_mov_b32_e32 v32, s15
	v_cndmask_b32_e64 v32, v177, v32, s[4:5]
	v_lshlrev_b32_e32 v32, 4, v32
	v_ashrrev_i32_e32 v33, 31, v32
	s_andn2_b64 vcc, exec, s[28:29]
	v_mad_u32_u24 v32, v32, 5, v249
	s_cbranch_vccnz .LBB0_252
	s_cmp_eq_u32 s13, 1
	s_cbranch_scc0 .LBB0_251
	ds_read_b128 v[34:37], v32
	ds_read_b128 v[38:41], v32 offset:16
	ds_read_b128 v[42:45], v32 offset:32
	ds_read_b128 v[46:49], v32 offset:48
	v_and_b32_e32 v52, 64, v181
	v_xor_b32_e32 v51, 32, v181
	v_add_u32_e32 v52, 64, v52
	v_cmp_lt_i32_e32 vcc, v51, v52
	v_mov_b32_e32 v50, v27
	s_waitcnt lgkmcnt(0)
	v_mov_b32_e32 v59, v36
	v_cndmask_b32_e32 v51, v181, v51, vcc
	v_lshlrev_b32_e32 v51, 2, v51
	ds_bpermute_b32 v54, v51, v30
	ds_bpermute_b32 v55, v51, v31
	ds_bpermute_b32 v58, v51, v26
	ds_bpermute_b32 v27, v51, v27
	ds_bpermute_b32 v52, v51, v28
	ds_bpermute_b32 v53, v51, v29
	ds_bpermute_b32 v56, v51, v24
	ds_bpermute_b32 v57, v51, v25
	s_waitcnt lgkmcnt(6)
	v_pk_mul_f32 v[54:55], v[140:141], v[54:55]
	s_waitcnt lgkmcnt(5)
	v_mul_f32_e32 v60, v140, v58
	s_waitcnt lgkmcnt(4)
	v_mul_f32_e32 v51, v140, v27
	v_mov_b32_e32 v36, v35
	v_mov_b32_e32 v35, v40
	v_mov_b32_e32 v40, v39
	s_waitcnt lgkmcnt(2)
	v_pk_mul_f32 v[52:53], v[140:141], v[52:53]
	s_waitcnt lgkmcnt(0)
	v_pk_mul_f32 v[56:57], v[140:141], v[56:57]
	v_mov_b32_e32 v58, v34
	v_mov_b32_e32 v34, v38
	v_pk_mul_f32 v[38:39], v[54:55], v[40:41]
	v_mov_b32_e32 v40, v42
	v_mov_b32_e32 v41, v44
	v_mov_b32_e32 v44, v43
	v_mul_f32_e32 v26, v26, v46
	v_mul_f32_e32 v42, v60, v47
	v_pk_mul_f32 v[46:47], v[50:51], v[48:49]
	v_pk_mul_f32 v[36:37], v[52:53], v[36:37]
	v_pk_mul_f32 v[44:45], v[56:57], v[44:45]
	v_mov_b32_e32 v27, v46
	v_mov_b32_e32 v43, v47
	v_pk_fma_f32 v[28:29], v[28:29], v[58:59], v[36:37]
	v_pk_fma_f32 v[30:31], v[30:31], v[34:35], v[38:39]
	v_pk_fma_f32 v[24:25], v[24:25], v[40:41], v[44:45]
	v_pk_add_f32 v[26:27], v[26:27], v[42:43]
	v_pk_mul_f32 v[36:37], s[22:23], v[30:31] op_sel_hi:[0,1]
	v_pk_mul_f32 v[34:35], s[22:23], v[28:29] op_sel_hi:[0,1]
	v_pk_mul_f32 v[40:41], s[22:23], v[26:27] op_sel_hi:[0,1]
	v_pk_mul_f32 v[38:39], s[22:23], v[24:25] op_sel_hi:[0,1]
	s_branch .LBB0_252

.LBB0_260:
	v_mov_b32_e32 v16, s15
	v_cndmask_b32_e64 v16, v179, v16, s[4:5]
	v_lshlrev_b32_e32 v16, 4, v16
	v_ashrrev_i32_e32 v17, 31, v16
	s_andn2_b64 vcc, exec, s[28:29]
	v_mad_u32_u24 v16, v16, 5, v249
	s_cbranch_vccnz .LBB0_264
	s_cmp_eq_u32 s13, 1
	s_cbranch_scc0 .LBB0_263
	ds_read_b128 v[18:21], v16
	ds_read_b128 v[22:25], v16 offset:16
	ds_read_b128 v[26:29], v16 offset:32
	ds_read_b128 v[30:33], v16 offset:48
	v_and_b32_e32 v36, 64, v181
	v_xor_b32_e32 v35, 32, v181
	v_add_u32_e32 v36, 64, v36
	v_cmp_lt_i32_e32 vcc, v35, v36
	v_mov_b32_e32 v34, v11
	s_waitcnt lgkmcnt(0)
	v_mov_b32_e32 v43, v20
	v_cndmask_b32_e32 v35, v181, v35, vcc
	v_lshlrev_b32_e32 v35, 2, v35
	ds_bpermute_b32 v38, v35, v14
	ds_bpermute_b32 v39, v35, v15
	ds_bpermute_b32 v42, v35, v10
	ds_bpermute_b32 v11, v35, v11
	ds_bpermute_b32 v36, v35, v12
	ds_bpermute_b32 v37, v35, v13
	ds_bpermute_b32 v40, v35, v8
	ds_bpermute_b32 v41, v35, v9
	s_waitcnt lgkmcnt(6)
	v_pk_mul_f32 v[38:39], v[140:141], v[38:39]
	s_waitcnt lgkmcnt(5)
	v_mul_f32_e32 v44, v140, v42
	s_waitcnt lgkmcnt(4)
	v_mul_f32_e32 v35, v140, v11
	v_mov_b32_e32 v20, v19
	v_mov_b32_e32 v19, v24
	v_mov_b32_e32 v24, v23
	s_waitcnt lgkmcnt(2)
	v_pk_mul_f32 v[36:37], v[140:141], v[36:37]
	s_waitcnt lgkmcnt(0)
	v_pk_mul_f32 v[40:41], v[140:141], v[40:41]
	v_mov_b32_e32 v42, v18
	v_mov_b32_e32 v18, v22
	v_pk_mul_f32 v[22:23], v[38:39], v[24:25]
	v_mov_b32_e32 v24, v26
	v_mov_b32_e32 v25, v28
	v_mov_b32_e32 v28, v27
	v_mul_f32_e32 v10, v10, v30
	v_mul_f32_e32 v26, v44, v31
	v_pk_mul_f32 v[30:31], v[34:35], v[32:33]
	v_pk_mul_f32 v[20:21], v[36:37], v[20:21]
	v_pk_mul_f32 v[28:29], v[40:41], v[28:29]
	v_mov_b32_e32 v11, v30
	v_mov_b32_e32 v27, v31
	v_pk_fma_f32 v[12:13], v[12:13], v[42:43], v[20:21]
	v_pk_fma_f32 v[14:15], v[14:15], v[18:19], v[22:23]
	v_pk_fma_f32 v[8:9], v[8:9], v[24:25], v[28:29]
	v_pk_add_f32 v[10:11], v[10:11], v[26:27]
	v_pk_mul_f32 v[20:21], s[22:23], v[14:15] op_sel_hi:[0,1]
	v_pk_mul_f32 v[18:19], s[22:23], v[12:13] op_sel_hi:[0,1]
	v_pk_mul_f32 v[24:25], s[22:23], v[10:11] op_sel_hi:[0,1]
	v_pk_mul_f32 v[22:23], s[22:23], v[8:9] op_sel_hi:[0,1]
	s_branch .LBB0_264
